# attention tile step re-scheduled by hand: V fragments moved off the score registers (mask thresholds recomputed inline), 24/32 exp2 + packs + row sums interleaved into the PV MFMA gaps, first V batche
# speedup vs baseline: 1.0242x; 1.0242x over previous
; __device__ __forceinline__ int opaque_tid() { int t = threadIdx.x; asm volatile("" : "+v"(t)); return t; }
; #define LAS __attribute__((address_space(3)))
; __device__ __forceinline__ void attn_phase(LAS unsigned char* lds, const bf16_t* Q, const bf16_t* Kimg, const bf16_t* Vimg, const bf16_t* Kmeta, const bf16_t* Vmeta,
;                                            bf16_t* O, const float* lamp, const float* sublnw, float lambda_init, int G) {
;     const int tid = opaque_tid(), lane = tid & 63, wid = __builtin_amdgcn_readfirstlane(tid >> 6), l31 = lane & 31, hi = lane >> 5;
;     const int qg = wid & 3, c = wid >> 2;
;     const int skew = (wid ^ (wid >> 2)) & 1;
;     float lam;
;     { const float a = lamp[lane] * lamp[64 + lane], b2 = lamp[128 + lane] * lamp[192 + lane]; lam = __expf(wave_sum(a)) - __expf(wave_sum(b2)) + lambda_init; }
;     const int kvrow = kvperm(l31);
;     LAS float* exch = (LAS float*)(lds + qg * 16384);
;     for (int item = blockIdx.x; item < 1024 + 8; item += G) {
;         for (int half = 0; half < 2; ++half) {
;             int b, h, qb; bool metaq = false;
;             if (item < 1024) {
;                 int bh = item >> 4, s = item & 15;
;                 if (G == 256) {
;                     const int v = item & 255, it = item >> 8, x = v & 7, t = v >> 3;
;                     bh = (it >> 1) * 32 + x * 4 + (t >> 3); s = (t & 7) + 8 * (it & 1);
;                 }
;                 b = bh >> 3; h = bh & 7; qb = half ? 31 - s : s; }
;             else { if (half) break; metaq = true; b = 0; h = item - 1024; qb = 0; }
;             const int NT = metaq ? 1 : 2 * qb + 3;
;             const bool active = !metaq || qg == 0;
;             const int qpos0 = metaq ? 0 : 16 + 128 * qb;
;             const int qrow = metaq ? MR + l31 : b * SEQ + 128 * qb + 32 * qg + l31;
;             const int qpos = metaq ? l31 : qpos0 + 32 * qg + l31;
;             const float slope2 = exp2f(-(float)(h + 1)) * LOG2E;
;             const bf16_t* Kbh = Kimg + (size_t)(b * 8 + h) * 64 * 8192; const bf16_t* Vbh = Vimg + (size_t)(b * 8 + h) * 64 * 8192;
;             const bf16_t* Kmh = Kmeta + (size_t)h * 8192; const bf16_t* Vmh = Vmeta + (size_t)h * 8192;
;             const unsigned ldsb = (unsigned)(uintptr_t)lds;
.LBB0_709:
	s_or_b64 exec, exec, s[8:9]
	s_mov_b64 s[8:9], s[90:91]
	s_waitcnt lgkmcnt(0)
	s_barrier
	s_load_dwordx4 s[16:19], s[8:9], 0x20
	s_lshl_b32 s2, s74, 8
	s_ashr_i32 s3, s2, 31
	s_lshl_b64 s[2:3], s[2:3], 2
	v_mov_b32_e32 v2, v194
	s_waitcnt lgkmcnt(0)
	s_add_u32 s4, s16, s2
	s_addc_u32 s5, s17, s3
	v_and_b32_e32 v0, 63, v2
	v_lshlrev_b32_e32 v3, 2, v0
	global_load_dword v4, v3, s[4:5]
	global_load_dword v5, v3, s[4:5] offset:256
	global_load_dword v7, v3, s[4:5] offset:512
	global_load_dword v8, v3, s[4:5] offset:768
	v_cmp_lt_i32_e32 vcc, v207, v201
	v_readlane_b32 s4, v253, 33
	v_readlane_b32 s5, v253, 34
	v_cndmask_b32_e32 v3, v200, v207, vcc
	v_lshlrev_b32_e32 v10, 2, v3
	v_cmp_lt_i32_e32 vcc, v206, v201
	v_readfirstlane_b32 s3, v2
	s_waitcnt vmcnt(2)
	v_mul_f32_e32 v6, v4, v5
	ds_bpermute_b32 v3, v10, v6
	s_waitcnt vmcnt(0)
	v_mul_f32_e32 v9, v7, v8
	ds_bpermute_b32 v9, v10, v9
	s_waitcnt lgkmcnt(1)
	v_fmac_f32_e32 v3, v4, v5
	v_cndmask_b32_e32 v4, v200, v206, vcc
	v_lshlrev_b32_e32 v5, 2, v4
	ds_bpermute_b32 v4, v5, v3
	s_waitcnt lgkmcnt(1)
	v_fmac_f32_e32 v9, v7, v8
	ds_bpermute_b32 v5, v5, v9
	s_waitcnt lgkmcnt(1)
	v_add_f32_e32 v3, v3, v4
	v_xor_b32_e32 v4, 4, v200
	v_cmp_lt_i32_e32 vcc, v4, v201
	s_waitcnt lgkmcnt(0)
	v_add_f32_e32 v5, v9, v5
	v_cndmask_b32_e32 v4, v200, v4, vcc
	v_lshlrev_b32_e32 v6, 2, v4
	ds_bpermute_b32 v4, v6, v3
	ds_bpermute_b32 v6, v6, v5
	s_waitcnt lgkmcnt(1)
	v_add_f32_e32 v3, v3, v4
	v_xor_b32_e32 v4, 8, v200
	v_cmp_lt_i32_e32 vcc, v4, v201
	s_waitcnt lgkmcnt(0)
	v_add_f32_e32 v5, v5, v6
	v_cndmask_b32_e32 v4, v200, v4, vcc
	v_lshlrev_b32_e32 v11, 2, v4
	ds_bpermute_b32 v4, v11, v3
	ds_bpermute_b32 v6, v11, v5
	s_waitcnt lgkmcnt(1)
	v_add_f32_e32 v3, v3, v4
	v_xor_b32_e32 v4, 16, v200
	v_cmp_lt_i32_e32 vcc, v4, v201
	s_waitcnt lgkmcnt(0)
	v_add_f32_e32 v5, v5, v6
	v_cndmask_b32_e32 v4, v200, v4, vcc
	v_lshlrev_b32_e32 v12, 2, v4
	ds_bpermute_b32 v4, v12, v3
	ds_bpermute_b32 v6, v12, v5
	s_waitcnt lgkmcnt(1)
	v_add_f32_e32 v3, v3, v4
	v_xor_b32_e32 v4, 32, v200
	v_cmp_lt_i32_e32 vcc, v4, v201
	s_waitcnt lgkmcnt(0)
	v_add_f32_e32 v5, v5, v6
	v_cndmask_b32_e32 v4, v200, v4, vcc
	v_lshlrev_b32_e32 v169, 2, v4
	ds_bpermute_b32 v4, v169, v3
	ds_bpermute_b32 v6, v169, v5
	s_andn2_b64 vcc, exec, s[4:5]
	s_cbranch_vccnz .LBB0_781
	s_load_dwordx2 s[4:5], s[8:9], 0x88
	v_lshlrev_b32_e32 v152, 4, v0
	v_mov_b32_e32 v153, v1
	s_waitcnt lgkmcnt(0)
	v_add_f32_e32 v3, v3, v4
	v_add_f32_e32 v4, v5, v6
	s_add_u32 s8, s4, 0x6400000
	s_addc_u32 s9, s5, 0
	s_add_u32 s76, s4, 0xa600000
	s_addc_u32 s77, s5, 0
	s_add_u32 s70, s4, 0xe700000
	v_writelane_b32 v255, s8, 2
	s_addc_u32 s71, s5, 0
	s_add_u32 s2, s4, 0x12700000
	v_writelane_b32 v255, s9, 3
	s_addc_u32 s66, s5, 0
	v_writelane_b32 v255, s74, 4
	s_lshl_b32 s8, s74, 7
	s_ashr_i32 s9, s8, 31
	s_lshl_b64 s[8:9], s[8:9], 2
	s_add_u32 s10, s18, s8
	s_addc_u32 s11, s19, s9
	s_ashr_i32 s6, s3, 6
	s_and_b32 s8, s6, 3
	s_lshl_b32 s9, s8, 14
	s_ashr_i32 s13, s3, 8
	s_add_i32 s12, s9, 0
	s_xor_b32 s9, s6, s13
	s_and_b32 s14, s9, 1
	s_cmp_eq_u32 s8, 0
	s_cselect_b64 s[16:17], -1, 0
	s_lshl_b32 s33, s6, 10
	s_lshl_b32 s67, s8, 5
	s_ashr_i32 s88, s33, 31
	s_add_u32 s4, s4, s33
	s_addc_u32 s5, s5, s88
	v_lshl_add_u64 v[162:163], s[4:5], 0, v[152:153]
	s_mov_b64 s[4:5], 0x16700000
	v_mul_f32_e32 v3, 0x3fb8aa3b, v3
	v_mul_f32_e32 v4, 0x3fb8aa3b, v4
	v_lshl_add_u64 v[164:165], v[162:163], 0, s[4:5]
	s_mov_b64 s[4:5], 0x16720000
	v_exp_f32_e32 v3, v3
	v_exp_f32_e32 v4, v4
	s_add_i32 s89, s33, 0
	v_lshl_add_u64 v[166:167], v[162:163], 0, s[4:5]
	s_add_i32 s4, 0, 0x10000
	s_lshl_b32 s80, s13, 6
	s_add_i32 s8, s33, s4
	s_add_i32 s9, s89, 0x4000
	s_add_i32 s68, s89, 0x14000
	s_add_i32 s69, s89, 0x8000
	s_ashr_i32 s81, s80, 31
	s_cmp_eq_u32 s14, 0
	v_mov_b32_e32 v5, 0x3ef1014c
	v_mov_b32_e32 v6, 0x3e4ccccd
	v_writelane_b32 v255, s75, 5
	s_cselect_b64 s[82:83], -1, 0
	s_cmp_eq_u32 s14, 1
	v_cndmask_b32_e64 v5, v5, v6, s[96:97]
	v_sub_f32_e32 v3, v3, v4
	v_writelane_b32 v255, s16, 6
	s_cselect_b64 s[84:85], -1, 0
	s_cmp_eq_u32 s13, 1
	v_add_f32_e32 v150, v5, v3
	v_lshrrev_b32_e32 v3, 1, v2
	v_and_b32_e32 v4, 19, v2
	v_and_b32_e32 v209, 31, v2
	v_lshlrev_b32_e32 v2, 1, v2
	v_writelane_b32 v255, s17, 7
	s_cselect_b64 s[14:15], -1, 0
	v_and_b32_e32 v3, 4, v3
	v_and_b32_e32 v2, 8, v2
	v_writelane_b32 v255, s14, 8
	s_cmpk_lt_u32 s3, 0x100
	v_or3_b32 v2, v3, v4, v2
	v_lshrrev_b32_e32 v3, 5, v0
	v_writelane_b32 v255, s15, 9
	s_cselect_b64 s[14:15], -1, 0
	v_lshl_add_u32 v211, v0, 2, s12
	v_writelane_b32 v255, s14, 10
	v_lshlrev_b32_e32 v0, 4, v3
	v_lshl_add_u32 v4, v2, 4, 0
	v_writelane_b32 v255, s15, 11
	v_lshl_add_u64 v[170:171], s[10:11], 0, v[0:1]
	v_subrev_co_u32_e64 v213, s[10:11], 16, v209
	s_lshl_b32 s3, s13, 13
	v_lshlrev_b32_e32 v0, 10, v3
	v_lshlrev_b32_e32 v168, 3, v3
	v_lshlrev_b32_e32 v6, 11, v3
	v_lshlrev_b32_e32 v7, 4, v209
	v_sub_f32_e32 v212, 1.0, v5
	v_lshlrev_b32_e32 v2, 2, v3
	v_writelane_b32 v255, s10, 12
	v_add_u32_e32 v3, s3, v4
	v_or_b32_e32 v5, s3, v0
	v_mov_b32_e32 v251, 0x2000
	v_mov_b32_e32 v252, 0x1000
	v_or_b32_e32 v210, 16, v168
	v_writelane_b32 v255, s11, 13
	v_or_b32_e32 v214, 2, v168
	v_or_b32_e32 v215, 3, v168
	v_or_b32_e32 v216, 4, v168
	v_or_b32_e32 v217, 5, v168
	v_or_b32_e32 v218, 6, v168
	v_or_b32_e32 v219, 7, v168
	v_add3_u32 v220, s4, v6, v7
	v_add_u32_e32 v221, v4, v5
	v_mov_b32_e32 v151, v150
	v_or_b32_e32 v244, 0x50, v168
	v_add_u32_e32 v245, v3, v0
	v_lshlrev_b32_e32 v172, 1, v2
	s_mov_b32 s3, s92
	s_branch .LBB0_712

; __device__ __forceinline__ float fexp2(float x) { return __builtin_amdgcn_exp2f(x); }
; __device__ __forceinline__ float max3f(float a, float b, float c) { float r; asm("v_max3_f32 %0, %1, %2, %3" : "=v"(r) : "v"(a), "v"(b), "v"(c)); return r; }
; __device__ __forceinline__ void attn_phase(LAS unsigned char* lds, const bf16_t* Q, const bf16_t* Kimg, const bf16_t* Vimg, const bf16_t* Kmeta, const bf16_t* Vmeta,
;                                            bf16_t* O, const float* lamp, const float* sublnw, float lambda_init, int G) {
;     ...
;                     if (j == 0 || j >= NT - 2) {
;                         const int kpos0 = (j == 0) ? 0 : 16 + 64 * (j - 1);
;                         const int lim = (j == 0) ? (metaq ? (l31 < 15 ? l31 : 15) : 15) : (qpos - kpos0);
; #pragma unroll
;                         for (int r = 0; r < 16; ++r) { const int kvl = 16 * (r >> 3) + (r & 7) + 8 * hi;
;                             if (kvl > lim) sA[r] = -INFINITY; if (kvl + 32 > lim) sB[r] = -INFINITY; }
;                     }
;                     float mxa = max3f(sA[0], sA[1], sA[2]), mxb = max3f(sB[0], sB[1], sB[2]);
; #pragma unroll
;                     for (int r = 3; r < 15; r += 2) { mxa = max3f(mxa, sA[r], sA[r + 1]); mxb = max3f(mxb, sB[r], sB[r + 1]); }
;                     float mx = max3f(mxa, mxb, sA[15]); mx = fmaxf(mx, sB[15]);
;                     mx = half_max(mx);
;                     alpha = 1.f;
;                     if (__any(mx > 64.f)) { const float d = fmaxf(mx, 0.f); alpha = fexp2(-d); mrun += d;
; #pragma unroll
;                         for (int r = 0; r < 16; ++r) { sA[r] -= d; sB[r] -= d; } }
.LBB0_756:
	s_cmp_lt_i32 s43, s42
	s_cbranch_scc1 .LBB0_758
	v_or_b32_e32 v2, 32, v168
	v_cmp_le_i32_e32 vcc, v2, v0
	s_nop 1
	v_cndmask_b32_e32 v34, v16, v34, vcc
	v_cmp_lt_i32_e32 vcc, v168, v0
	s_nop 1
	v_cndmask_b32_e32 v19, v16, v19, vcc
	v_cmp_le_i32_e32 vcc, v168, v0
	s_nop 1
	v_cndmask_b32_e32 v18, v16, v18, vcc
	v_or_b32_e32 v192, 33, v168
	v_cmp_le_i32_e32 vcc, v192, v0
	s_nop 1
	v_cndmask_b32_e32 v35, v16, v35, vcc
	v_cmp_le_i32_e32 vcc, v214, v0
	s_nop 1
	v_cndmask_b32_e32 v20, v16, v20, vcc
	v_or_b32_e32 v192, 34, v168
	v_cmp_le_i32_e32 vcc, v192, v0
	s_nop 1
	v_cndmask_b32_e32 v36, v16, v36, vcc
	v_cmp_le_i32_e32 vcc, v215, v0
	s_nop 1
	v_cndmask_b32_e32 v21, v16, v21, vcc
	v_or_b32_e32 v192, 35, v168
	v_cmp_le_i32_e32 vcc, v192, v0
	s_nop 1
	v_cndmask_b32_e32 v37, v16, v37, vcc
	v_cmp_le_i32_e32 vcc, v216, v0
	s_nop 1
	v_cndmask_b32_e32 v22, v16, v22, vcc
	v_or_b32_e32 v192, 36, v168
	v_cmp_le_i32_e32 vcc, v192, v0
	s_nop 1
	v_cndmask_b32_e32 v38, v16, v38, vcc
	v_cmp_le_i32_e32 vcc, v217, v0
	s_nop 1
	v_cndmask_b32_e32 v23, v16, v23, vcc
	v_or_b32_e32 v192, 37, v168
	v_cmp_le_i32_e32 vcc, v192, v0
	s_nop 1
	v_cndmask_b32_e32 v39, v16, v39, vcc
	v_cmp_le_i32_e32 vcc, v218, v0
	s_nop 1
	v_cndmask_b32_e32 v24, v16, v24, vcc
	v_or_b32_e32 v192, 38, v168
	v_cmp_le_i32_e32 vcc, v192, v0
	s_nop 1
	v_cndmask_b32_e32 v40, v16, v40, vcc
	v_cmp_le_i32_e32 vcc, v219, v0
	s_nop 1
	v_cndmask_b32_e32 v25, v16, v25, vcc
	v_or_b32_e32 v192, 39, v168
	v_cmp_le_i32_e32 vcc, v192, v0
	s_nop 1
	v_cndmask_b32_e32 v41, v16, v41, vcc
	v_cmp_le_i32_e32 vcc, v210, v0
	s_nop 1
	v_cndmask_b32_e32 v26, v16, v26, vcc
	v_or_b32_e32 v192, 48, v168
	v_cmp_le_i32_e32 vcc, v192, v0
	s_nop 1
	v_cndmask_b32_e32 v42, v16, v42, vcc
	v_or_b32_e32 v192, 17, v168
	v_cmp_le_i32_e32 vcc, v192, v0
	s_nop 1
	v_cndmask_b32_e32 v27, v16, v27, vcc
	v_or_b32_e32 v192, 49, v168
	v_cmp_le_i32_e32 vcc, v192, v0
	s_nop 1
	v_cndmask_b32_e32 v43, v16, v43, vcc
	v_or_b32_e32 v192, 18, v168
	v_cmp_le_i32_e32 vcc, v192, v0
	s_nop 1
	v_cndmask_b32_e32 v28, v16, v28, vcc
	v_or_b32_e32 v192, 50, v168
	v_cmp_le_i32_e32 vcc, v192, v0
	s_nop 1
	v_cndmask_b32_e32 v44, v16, v44, vcc
	v_or_b32_e32 v192, 19, v168
	v_cmp_le_i32_e32 vcc, v192, v0
	s_nop 1
	v_cndmask_b32_e32 v29, v16, v29, vcc
	v_or_b32_e32 v192, 51, v168
	v_cmp_le_i32_e32 vcc, v192, v0
	s_nop 1
	v_cndmask_b32_e32 v45, v16, v45, vcc
	v_or_b32_e32 v192, 20, v168
	v_cmp_le_i32_e32 vcc, v192, v0
	s_nop 1
	v_cndmask_b32_e32 v30, v16, v30, vcc
	v_or_b32_e32 v192, 52, v168
	v_cmp_le_i32_e32 vcc, v192, v0
	s_nop 1
	v_cndmask_b32_e32 v46, v16, v46, vcc
	v_or_b32_e32 v192, 21, v168
	v_cmp_le_i32_e32 vcc, v192, v0
	s_nop 1
	v_cndmask_b32_e32 v31, v16, v31, vcc
	v_or_b32_e32 v192, 53, v168
	v_cmp_le_i32_e32 vcc, v192, v0
	s_nop 1
	v_cndmask_b32_e32 v47, v16, v47, vcc
	v_or_b32_e32 v192, 22, v168
	v_cmp_le_i32_e32 vcc, v192, v0
	s_nop 1
	v_cndmask_b32_e32 v32, v16, v32, vcc
	v_or_b32_e32 v192, 54, v168
	v_cmp_le_i32_e32 vcc, v192, v0
	s_nop 1
	v_cndmask_b32_e32 v48, v16, v48, vcc
	v_or_b32_e32 v192, 23, v168
	v_cmp_le_i32_e32 vcc, v192, v0
	s_nop 1
	v_cndmask_b32_e32 v33, v16, v33, vcc
	v_or_b32_e32 v192, 55, v168
	v_cmp_le_i32_e32 vcc, v192, v0
	s_nop 1
	v_cndmask_b32_e32 v49, v16, v49, vcc
.LBB0_758:
	s_add_i32 s10, s38, 0x4000
	s_and_b32 s10, s10, 0xc000
	v_add_u32_e32 v234, s10, v220
	ds_read_b128 v[184:187], v234
	ds_read_b128 v[188:191], v234 offset:512
	ds_read_b128 v[202:205], v234 offset:1024
	ds_read_b128 v[246:249], v234 offset:1536
	ds_read_b128 v[196:199], v234 offset:4096
	ds_read_b128 v[222:225], v234 offset:4608
	ds_read_b128 v[226:229], v234 offset:5120
	ds_read_b128 v[230:233], v234 offset:5632
	v_max3_f32 v2, v18, v19, v20
	v_max3_f32 v3, v34, v35, v36
	s_nop 0
	v_max3_f32 v2, v2, v21, v22
	v_max3_f32 v3, v3, v37, v38
	s_nop 0
	v_max3_f32 v2, v2, v23, v24
	v_max3_f32 v3, v3, v39, v40
	s_nop 0
	v_max3_f32 v2, v2, v25, v26
	v_max3_f32 v3, v3, v41, v42
	s_nop 0
	v_max3_f32 v2, v2, v27, v28
	v_max3_f32 v3, v3, v43, v44
	s_nop 0
	v_max3_f32 v2, v2, v29, v30
	v_max3_f32 v3, v3, v45, v46
	s_nop 0
	v_max3_f32 v2, v2, v31, v32
	v_max3_f32 v3, v3, v47, v48
	s_nop 0
	v_max3_f32 v2, v2, v3, v33
	v_max_f32_e32 v3, v49, v49
	v_max_f32_e32 v2, v2, v2
	v_max_f32_e32 v2, v2, v3
	v_mov_b32_e32 v3, v2
	s_nop 1
	v_permlane32_swap_b32_e32 v2, v3
	v_max_f32_e32 v3, v3, v3
	v_max_f32_e32 v2, v2, v2
	v_max_f32_e32 v2, v2, v3
	v_cmp_lt_f32_e32 vcc, s45, v2
	s_cbranch_vccz .LBB0_760
	v_max_f32_e32 v2, v2, v2
	v_max_f32_e32 v2, 0, v2
	v_exp_f32_e64 v178, -v2
	v_pk_add_f32 v[18:19], v[18:19], v[2:3] op_sel_hi:[1,0] neg_lo:[0,1] neg_hi:[0,1]
	v_pk_add_f32 v[34:35], v[34:35], v[2:3] op_sel_hi:[1,0] neg_lo:[0,1] neg_hi:[0,1]
	v_pk_add_f32 v[20:21], v[20:21], v[2:3] op_sel_hi:[1,0] neg_lo:[0,1] neg_hi:[0,1]
	v_pk_add_f32 v[36:37], v[36:37], v[2:3] op_sel_hi:[1,0] neg_lo:[0,1] neg_hi:[0,1]
	v_pk_add_f32 v[22:23], v[22:23], v[2:3] op_sel_hi:[1,0] neg_lo:[0,1] neg_hi:[0,1]
	v_pk_add_f32 v[38:39], v[38:39], v[2:3] op_sel_hi:[1,0] neg_lo:[0,1] neg_hi:[0,1]
	v_pk_add_f32 v[24:25], v[24:25], v[2:3] op_sel_hi:[1,0] neg_lo:[0,1] neg_hi:[0,1]
	v_pk_add_f32 v[40:41], v[40:41], v[2:3] op_sel_hi:[1,0] neg_lo:[0,1] neg_hi:[0,1]
	v_pk_add_f32 v[26:27], v[26:27], v[2:3] op_sel_hi:[1,0] neg_lo:[0,1] neg_hi:[0,1]
	v_pk_add_f32 v[42:43], v[42:43], v[2:3] op_sel_hi:[1,0] neg_lo:[0,1] neg_hi:[0,1]
	v_pk_add_f32 v[28:29], v[28:29], v[2:3] op_sel_hi:[1,0] neg_lo:[0,1] neg_hi:[0,1]
	v_pk_add_f32 v[44:45], v[44:45], v[2:3] op_sel_hi:[1,0] neg_lo:[0,1] neg_hi:[0,1]
	v_pk_add_f32 v[30:31], v[30:31], v[2:3] op_sel_hi:[1,0] neg_lo:[0,1] neg_hi:[0,1]
	v_pk_add_f32 v[46:47], v[46:47], v[2:3] op_sel_hi:[1,0] neg_lo:[0,1] neg_hi:[0,1]
	v_pk_add_f32 v[32:33], v[32:33], v[2:3] op_sel_hi:[1,0] neg_lo:[0,1] neg_hi:[0,1]
	v_pk_add_f32 v[48:49], v[48:49], v[2:3] op_sel_hi:[1,0] neg_lo:[0,1] neg_hi:[0,1]
	v_add_f32_e32 v173, v173, v2
	s_branch .LBB0_761

; __device__ __forceinline__ unsigned pk_bf16(float lo, float hi) { f32x2_t v = {lo, hi}; bf16x2_t b = __builtin_convertvector(v, bf16x2_t); return __builtin_bit_cast(unsigned, b); }
; __device__ __forceinline__ float fexp2(float x) { return __builtin_amdgcn_exp2f(x); }
; __device__ __forceinline__ void attn_phase(LAS unsigned char* lds, const bf16_t* Q, const bf16_t* Kimg, const bf16_t* Vimg, const bf16_t* Kmeta, const bf16_t* Vmeta,
;                                            bf16_t* O, const float* lamp, const float* sublnw, float lambda_init, int G) {
;     ...
;                     float ps = 0.f;
; #pragma unroll
;                     for (int q4 = 0; q4 < 8; ++q4) {
;                         const float a0 = fexp2(sA[2 * q4]), a1 = fexp2(sA[2 * q4 + 1]), b0 = fexp2(sB[2 * q4]), b1 = fexp2(sB[2 * q4 + 1]);
;                         ps += (a0 + a1) + (b0 + b1);
;                         pk[q4 >> 2][q4 & 3] = pk_bf16(a0, a1); pk[2 + (q4 >> 2)][q4 & 3] = pk_bf16(b0, b1); }
;                     lrun = lrun * alpha + ps;
.LBB0_761:
	v_exp_f32_e32 v3, v18
	v_exp_f32_e32 v5, v19
	v_exp_f32_e32 v4, v20
	v_exp_f32_e32 v2, v21
	v_exp_f32_e32 v6, v22
	v_exp_f32_e32 v7, v23
	v_exp_f32_e32 v8, v24
	v_exp_f32_e32 v9, v25
	v_cvt_pk_bf16_f32 v138, v3, v5
	v_cvt_pk_bf16_f32 v139, v4, v2
	v_cvt_pk_bf16_f32 v140, v6, v7
	v_cvt_pk_bf16_f32 v141, v8, v9
	v_add_f32_e32 v236, v3, v5
	v_add_f32_e32 v237, v4, v2
	v_add_f32_e32 v238, v6, v7
	v_add_f32_e32 v239, v8, v9
	s_and_b64 vcc, exec, s[34:35]
	s_cbranch_vccnz .LBB0_766

; #define VFR(F, s4) _Pragma("unroll") for (int i = 0; i < 4; ++i) F[i] = *(const LAS bf16x8*)(Vb + (2 * (s4) + hi) * 2048 + (32 * i + l31) * 16)
; __device__ __forceinline__ void attn_phase(LAS unsigned char* lds, const bf16_t* Q, const bf16_t* Kimg, const bf16_t* Vimg, const bf16_t* Kmeta, const bf16_t* Vmeta,
;                                            bf16_t* O, const float* lamp, const float* sublnw, float lambda_init, int G) {
;     ...
;                     __builtin_amdgcn_s_setprio(1);
;                     VFR(fa, 0);
;                     if (__any(alpha != 1.f)) {
; #pragma unroll
;                         for (int d = 0; d < 4; ++d)
; #pragma unroll
;                             for (int r = 0; r < 16; ++r) o[d][r] *= alpha;
;                     }
.LBB0_766:
	s_and_b64 vcc, exec, s[30:31]
	s_cbranch_vccnz .LBB0_770
	s_setprio 1
	v_cmp_neq_f32_e32 vcc, 1.0, v178
	s_cbranch_vccz .Latt_noalpha
	v_pk_mul_f32 v[112:113], v[112:113], v[178:179] op_sel_hi:[1,0]
	v_pk_mul_f32 v[110:111], v[110:111], v[178:179] op_sel_hi:[1,0]
	v_pk_mul_f32 v[108:109], v[108:109], v[178:179] op_sel_hi:[1,0]
	v_pk_mul_f32 v[106:107], v[106:107], v[178:179] op_sel_hi:[1,0]
	v_pk_mul_f32 v[104:105], v[104:105], v[178:179] op_sel_hi:[1,0]
	v_pk_mul_f32 v[102:103], v[102:103], v[178:179] op_sel_hi:[1,0]
	v_pk_mul_f32 v[100:101], v[100:101], v[178:179] op_sel_hi:[1,0]
	v_pk_mul_f32 v[98:99], v[98:99], v[178:179] op_sel_hi:[1,0]
	v_pk_mul_f32 v[96:97], v[96:97], v[178:179] op_sel_hi:[1,0]
	v_pk_mul_f32 v[94:95], v[94:95], v[178:179] op_sel_hi:[1,0]
	v_pk_mul_f32 v[92:93], v[92:93], v[178:179] op_sel_hi:[1,0]
	v_pk_mul_f32 v[90:91], v[90:91], v[178:179] op_sel_hi:[1,0]
	v_pk_mul_f32 v[88:89], v[88:89], v[178:179] op_sel_hi:[1,0]
	v_pk_mul_f32 v[86:87], v[86:87], v[178:179] op_sel_hi:[1,0]
	v_pk_mul_f32 v[84:85], v[84:85], v[178:179] op_sel_hi:[1,0]
	v_pk_mul_f32 v[82:83], v[82:83], v[178:179] op_sel_hi:[1,0]
	v_pk_mul_f32 v[80:81], v[80:81], v[178:179] op_sel_hi:[1,0]
	v_pk_mul_f32 v[78:79], v[78:79], v[178:179] op_sel_hi:[1,0]
	v_pk_mul_f32 v[76:77], v[76:77], v[178:179] op_sel_hi:[1,0]
	v_pk_mul_f32 v[74:75], v[74:75], v[178:179] op_sel_hi:[1,0]
	v_pk_mul_f32 v[72:73], v[72:73], v[178:179] op_sel_hi:[1,0]
	v_pk_mul_f32 v[70:71], v[70:71], v[178:179] op_sel_hi:[1,0]
	v_pk_mul_f32 v[68:69], v[68:69], v[178:179] op_sel_hi:[1,0]
	v_pk_mul_f32 v[66:67], v[66:67], v[178:179] op_sel_hi:[1,0]
	v_pk_mul_f32 v[64:65], v[64:65], v[178:179] op_sel_hi:[1,0]
	v_pk_mul_f32 v[62:63], v[62:63], v[178:179] op_sel_hi:[1,0]
	v_pk_mul_f32 v[60:61], v[60:61], v[178:179] op_sel_hi:[1,0]
	v_pk_mul_f32 v[58:59], v[58:59], v[178:179] op_sel_hi:[1,0]
	v_pk_mul_f32 v[56:57], v[56:57], v[178:179] op_sel_hi:[1,0]
	v_pk_mul_f32 v[54:55], v[54:55], v[178:179] op_sel_hi:[1,0]
	v_pk_mul_f32 v[52:53], v[52:53], v[178:179] op_sel_hi:[1,0]
	v_pk_mul_f32 v[50:51], v[50:51], v[178:179] op_sel_hi:[1,0]
; #define LAS __attribute__((address_space(3)))
; __device__ __forceinline__ unsigned pk_bf16(float lo, float hi) { f32x2_t v = {lo, hi}; bf16x2_t b = __builtin_convertvector(v, bf16x2_t); return __builtin_bit_cast(unsigned, b); }
; __device__ __forceinline__ float fexp2(float x) { return __builtin_amdgcn_exp2f(x); }
; #define SBAR __builtin_amdgcn_sched_barrier(0)
; __device__ __forceinline__ void attn_phase(LAS unsigned char* lds, const bf16_t* Q, const bf16_t* Kimg, const bf16_t* Vimg, const bf16_t* Kmeta, const bf16_t* Vmeta,
;                                            bf16_t* O, const float* lamp, const float* sublnw, float lambda_init, int G) {
;     ...
;                     float ps = 0.f;
; #pragma unroll
;                     for (int q4 = 0; q4 < 8; ++q4) {
;                         const float a0 = fexp2(sA[2 * q4]), a1 = fexp2(sA[2 * q4 + 1]), b0 = fexp2(sB[2 * q4]), b1 = fexp2(sB[2 * q4 + 1]);
;                         ps += (a0 + a1) + (b0 + b1);
;                         pk[q4 >> 2][q4 & 3] = pk_bf16(a0, a1); pk[2 + (q4 >> 2)][q4 & 3] = pk_bf16(b0, b1); }
;                     lrun = lrun * alpha + ps;
;                 }
;                 if (skew == 1) { if (j + 3 < NT) WAITV_BAR(4); else WAITV_BAR(0); }
;                 if (active) {
;                     const LAS unsigned char* Vb = lds + 65536 + (j & 3) * 16384;
;                     const LAS unsigned char* Kb = lds + ((j + 1) & 3) * 16384;
;                     bf16x8 fa[4], fb[4];
;     ...
;                     __builtin_amdgcn_s_setprio(1);
;                     VFR(fa, 0);
;                     if (__any(alpha != 1.f)) {
; #pragma unroll
;                         for (int d = 0; d < 4; ++d)
; #pragma unroll
;                             for (int r = 0; r < 16; ++r) o[d][r] *= alpha;
;                     }
;                     SBAR; VFR(fb, 1); SBAR; PVM(fa, 0); SBAR; VFR(fa, 2); SBAR; PVM(fb, 1); SBAR; VFR(fb, 3); SBAR; PVM(fa, 2); SBAR; KFR(fa, 0); SBAR; PVM(fb, 3); SBAR; KFR(fb, 1);
;                     { const int kp0_ = 16 + 64 * j; const float tb_ = slope2 * (float)(kp0_ - qpos0 + 8 * hi) - mrun;
; #pragma unroll
;                       for (int r = 0; r < 16; ++r) { sA[r] = fmaf(slope2, (float)(16 * (r >> 3) + (r & 7)), tb_); sB[r] = fmaf(slope2, (float)(32 + 16 * (r >> 3) + (r & 7)), tb_); } }
;                     SBAR; QKM(fa, 0); SBAR; QKM(fb, 1);
.Latt_noalpha:
	s_waitcnt lgkmcnt(7)
	v_mfma_f32_32x32x16_bf16 v[98:113], v[184:187], v[138:141], v[98:113]
	v_exp_f32_e32 v3, v26
	v_exp_f32_e32 v5, v27
	s_waitcnt lgkmcnt(6)
	v_mfma_f32_32x32x16_bf16 v[82:97], v[188:191], v[138:141], v[82:97]
	v_exp_f32_e32 v4, v28
	v_exp_f32_e32 v2, v29
	s_waitcnt lgkmcnt(5)
	v_mfma_f32_32x32x16_bf16 v[66:81], v[202:205], v[138:141], v[66:81]
	v_exp_f32_e32 v6, v30
	v_exp_f32_e32 v7, v31
	s_waitcnt lgkmcnt(4)
	v_mfma_f32_32x32x16_bf16 v[50:65], v[246:249], v[138:141], v[50:65]
	v_exp_f32_e32 v8, v32
	v_exp_f32_e32 v9, v33
	ds_read_b128 v[184:187], v234 offset:8192
	ds_read_b128 v[188:191], v234 offset:8704
	ds_read_b128 v[202:205], v234 offset:9216
	ds_read_b128 v[246:249], v234 offset:9728
	v_cvt_pk_bf16_f32 v142, v3, v5
	v_cvt_pk_bf16_f32 v143, v4, v2
	v_cvt_pk_bf16_f32 v144, v6, v7
	v_cvt_pk_bf16_f32 v145, v8, v9
	v_add_f32_e32 v240, v3, v5
	v_add_f32_e32 v241, v4, v2
	v_add_f32_e32 v242, v6, v7
	v_add_f32_e32 v243, v8, v9
	s_waitcnt lgkmcnt(7)
	v_mfma_f32_32x32x16_bf16 v[98:113], v[196:199], v[142:145], v[98:113]
	v_exp_f32_e32 v3, v34
	v_exp_f32_e32 v5, v35
	s_waitcnt lgkmcnt(6)
	v_mfma_f32_32x32x16_bf16 v[82:97], v[222:225], v[142:145], v[82:97]
	v_exp_f32_e32 v4, v36
	v_exp_f32_e32 v2, v37
	s_waitcnt lgkmcnt(5)
	v_mfma_f32_32x32x16_bf16 v[66:81], v[226:229], v[142:145], v[66:81]
	v_exp_f32_e32 v6, v38
	v_exp_f32_e32 v7, v39
	s_waitcnt lgkmcnt(4)
	v_mfma_f32_32x32x16_bf16 v[50:65], v[230:233], v[142:145], v[50:65]
	v_exp_f32_e32 v8, v40
	v_exp_f32_e32 v9, v41
	ds_read_b128 v[196:199], v234 offset:12288
	ds_read_b128 v[222:225], v234 offset:12800
	ds_read_b128 v[226:229], v234 offset:13312
	ds_read_b128 v[230:233], v234 offset:13824
	v_cvt_pk_bf16_f32 v134, v3, v5
	v_cvt_pk_bf16_f32 v135, v4, v2
	v_cvt_pk_bf16_f32 v136, v6, v7
	v_cvt_pk_bf16_f32 v137, v8, v9
	v_add_f32_e32 v11, v3, v5
	v_add_f32_e32 v12, v4, v2
	v_add_f32_e32 v13, v6, v7
	v_add_f32_e32 v192, v8, v9
	s_waitcnt lgkmcnt(7)
	v_mfma_f32_32x32x16_bf16 v[98:113], v[184:187], v[134:137], v[98:113]
	v_exp_f32_e32 v3, v42
	v_exp_f32_e32 v5, v43
	v_add_f32_e32 v236, v11, v236
	s_waitcnt lgkmcnt(6)
	v_mfma_f32_32x32x16_bf16 v[82:97], v[188:191], v[134:137], v[82:97]
	v_exp_f32_e32 v4, v44
	v_exp_f32_e32 v2, v45
	v_add_f32_e32 v237, v12, v237
	s_waitcnt lgkmcnt(5)
	v_mfma_f32_32x32x16_bf16 v[66:81], v[202:205], v[134:137], v[66:81]
	v_exp_f32_e32 v6, v46
	v_exp_f32_e32 v7, v47
	v_add_f32_e32 v10, v237, v236
	v_add_f32_e32 v238, v13, v238
	s_waitcnt lgkmcnt(4)
	v_mfma_f32_32x32x16_bf16 v[50:65], v[246:249], v[134:137], v[50:65]
	v_exp_f32_e32 v8, v48
	v_exp_f32_e32 v9, v49
	v_add_f32_e32 v239, v192, v239
	v_add_f32_e32 v10, v238, v10
	s_add_i32 s10, s38, 0x8000
	s_and_b32 s10, s10, 0xc000
	v_add_u32_e32 v235, s10, v221
	ds_read_b128 v[184:187], v235
	ds_read_b128 v[188:191], v235 offset:512
	ds_read_b128 v[202:205], v235 offset:2048
	ds_read_b128 v[246:249], v235 offset:2560
	v_cvt_pk_bf16_f32 v146, v3, v5
	v_cvt_pk_bf16_f32 v147, v4, v2
	v_cvt_pk_bf16_f32 v148, v6, v7
	v_cvt_pk_bf16_f32 v149, v8, v9
	v_add_f32_e32 v11, v3, v5
	v_add_f32_e32 v12, v4, v2
	v_add_f32_e32 v13, v6, v7
	v_add_f32_e32 v192, v8, v9
	v_add_f32_e32 v10, v239, v10
	s_waitcnt lgkmcnt(7)
	v_mfma_f32_32x32x16_bf16 v[98:113], v[196:199], v[146:149], v[98:113]
	v_add_f32_e32 v240, v11, v240
	v_add_f32_e32 v10, v240, v10
	s_waitcnt lgkmcnt(6)
	v_mfma_f32_32x32x16_bf16 v[82:97], v[222:225], v[146:149], v[82:97]
	v_add_f32_e32 v241, v12, v241
	v_add_f32_e32 v10, v241, v10
	s_waitcnt lgkmcnt(5)
	v_mfma_f32_32x32x16_bf16 v[66:81], v[226:229], v[146:149], v[66:81]
	v_add_f32_e32 v242, v13, v242
	v_add_f32_e32 v10, v242, v10
	s_waitcnt lgkmcnt(4)
	v_mfma_f32_32x32x16_bf16 v[50:65], v[230:233], v[146:149], v[50:65]
	v_add_f32_e32 v243, v192, v243
	v_add_f32_e32 v10, v243, v10
	v_fma_f32 v17, v17, v178, v10
	ds_read_b128 v[196:199], v235 offset:4096
	ds_read_b128 v[222:225], v235 offset:4608
	ds_read_b128 v[226:229], v235 offset:6144
	ds_read_b128 v[230:233], v235 offset:6656
	v_cvt_f32_i32_e32 v19, v179
	v_mov_b32_e32 v177, v176
	s_nop 0
	v_fma_f32 v34, v176, v19, -v173
	v_fma_f32 v18, 0, v176, v34
	v_add_f32_e32 v19, v176, v34
	v_fmamk_f32 v20, v176, 0x40000000, v34
	v_fmamk_f32 v21, v176, 0x40400000, v34
	v_fmamk_f32 v22, v176, 0x40800000, v34
	v_fmamk_f32 v23, v176, 0x40a00000, v34
	v_fmamk_f32 v24, v176, 0x40c00000, v34
	v_fmamk_f32 v25, v176, 0x40e00000, v34
	v_fmamk_f32 v26, v176, 0x41800000, v34
	v_fmamk_f32 v27, v176, 0x41880000, v34
	v_fmamk_f32 v28, v176, 0x41900000, v34
	v_fmamk_f32 v29, v176, 0x41980000, v34
	v_fmamk_f32 v30, v176, 0x41a00000, v34
	v_fmamk_f32 v31, v176, 0x41a80000, v34
	v_fmamk_f32 v32, v176, 0x41b00000, v34
	v_fmamk_f32 v33, v176, 0x41b80000, v34
	v_fmamk_f32 v49, v176, 0x425c0000, v34
	v_fmamk_f32 v48, v176, 0x42580000, v34
	v_fmamk_f32 v47, v176, 0x42540000, v34
	v_fmamk_f32 v46, v176, 0x42500000, v34
	v_fmamk_f32 v45, v176, 0x424c0000, v34
	v_fmamk_f32 v44, v176, 0x42480000, v34
	v_fmamk_f32 v43, v176, 0x42440000, v34
	v_fmamk_f32 v42, v176, 0x42400000, v34
	v_fmamk_f32 v41, v176, 0x421c0000, v34
	v_fmamk_f32 v40, v176, 0x42180000, v34
	v_fmamk_f32 v39, v176, 0x42140000, v34
	v_fmamk_f32 v38, v176, 0x42100000, v34
	v_fmamk_f32 v37, v176, 0x420c0000, v34
	v_fmamk_f32 v36, v176, 0x42080000, v34
	v_fmamk_f32 v35, v176, 0x42040000, v34
	v_fmamk_f32 v34, v176, 0x42000000, v34
	s_waitcnt lgkmcnt(7)
	v_mfma_f32_32x32x16_bf16 v[18:33], v[184:187], v[118:121], v[18:33]
	s_waitcnt lgkmcnt(6)
	v_mfma_f32_32x32x16_bf16 v[34:49], v[188:191], v[118:121], v[34:49]
	s_waitcnt lgkmcnt(5)
	v_mfma_f32_32x32x16_bf16 v[18:33], v[202:205], v[122:125], v[18:33]
	s_waitcnt lgkmcnt(4)
	v_mfma_f32_32x32x16_bf16 v[34:49], v[246:249], v[122:125], v[34:49]
	s_waitcnt lgkmcnt(3)
	v_mfma_f32_32x32x16_bf16 v[18:33], v[196:199], v[126:129], v[18:33]
	s_waitcnt lgkmcnt(2)
	v_mfma_f32_32x32x16_bf16 v[34:49], v[222:225], v[126:129], v[34:49]
	s_waitcnt lgkmcnt(1)
	v_mfma_f32_32x32x16_bf16 v[18:33], v[226:229], v[130:133], v[18:33]
	s_waitcnt lgkmcnt(0)
	v_mfma_f32_32x32x16_bf16 v[34:49], v[230:233], v[130:133], v[34:49]
	s_setprio 0
